# merge step: gates of next segment reused instead of reloaded, accumulators scaled directly; gla_out step batched loads
# speedup vs baseline: 1.0519x; 1.0519x over previous
.LBB0_111:
	s_mov_b64 s[2:3], 0x400
	s_add_i32 s10, s10, 1
	v_lshl_add_u64 v[90:91], v[90:91], 0, s[2:3]
	s_mov_b64 s[2:3], 0x100000
	s_cmp_eq_u32 s10, 3
	v_lshl_add_u64 v[92:93], v[92:93], 0, s[2:3]
	s_cbranch_scc1 .LBB0_96
.LBB0_112:
	s_lshl_b32 s2, s10, 10
	s_lshl_b32 s16, s10, 9
	s_add_i32 s12, s2, 0x400
	s_cmp_lg_u32 s10, 2
	s_cselect_b64 s[2:3], -1, 0
	s_and_b64 s[4:5], s[2:3], exec
	s_cselect_b32 s4, s12, 0x800
	s_lshl_b32 s12, s10, 11
	v_lshl_add_u64 v[4:5], v[84:85], 0, s[12:13]
	s_lshl_b32 s4, s4, 1
	s_mov_b32 s5, s13
	v_lshl_add_u64 v[6:7], v[84:85], 0, s[4:5]
	s_cmp_eq_u32 s10, 0
	s_cbranch_scc0 .Lmg_reuse
	global_load_dwordx2 v[140:141], v[4:5], off
	global_load_dwordx2 v[106:107], v[4:5], off offset:32
	global_load_dwordx2 v[114:115], v[4:5], off offset:64
	global_load_dwordx2 v[122:123], v[4:5], off offset:96
	global_load_dwordx2 v[102:103], v[6:7], off
	global_load_dwordx2 v[110:111], v[6:7], off offset:32
	global_load_dwordx2 v[120:121], v[6:7], off offset:64
	global_load_dwordx2 v[128:129], v[6:7], off offset:96
	v_lshl_add_u64 v[4:5], v[86:87], 0, s[12:13]
	v_lshl_add_u64 v[6:7], v[86:87], 0, s[4:5]
	global_load_dwordx2 v[130:131], v[4:5], off
	global_load_dwordx2 v[138:139], v[4:5], off offset:32
	global_load_dwordx2 v[132:133], v[4:5], off offset:64
	global_load_dwordx2 v[124:125], v[4:5], off offset:96
	global_load_dwordx2 v[136:137], v[6:7], off
	global_load_dwordx2 v[134:135], v[6:7], off offset:32
	global_load_dwordx2 v[126:127], v[6:7], off offset:64
	global_load_dwordx2 v[118:119], v[6:7], off offset:96
	v_lshl_add_u64 v[4:5], v[88:89], 0, s[12:13]
	v_lshl_add_u64 v[6:7], v[88:89], 0, s[4:5]
	global_load_dwordx2 v[116:117], v[4:5], off
	global_load_dwordx2 v[108:109], v[4:5], off offset:32
	global_load_dwordx2 v[100:101], v[4:5], off offset:64
	global_load_dwordx2 v[96:97], v[4:5], off offset:96
	global_load_dwordx2 v[112:113], v[6:7], off
	global_load_dwordx2 v[104:105], v[6:7], off offset:32
	global_load_dwordx2 v[98:99], v[6:7], off offset:64
	global_load_dwordx2 v[94:95], v[6:7], off offset:96
	s_branch .Lmg_ld_done
.Lmg_reuse:
	v_mov_b32_e32 v140, v102
	v_mov_b32_e32 v106, v110
	v_mov_b32_e32 v114, v120
	v_mov_b32_e32 v122, v128
	v_mov_b32_e32 v130, v136
	v_mov_b32_e32 v138, v134
	v_mov_b32_e32 v132, v126
	v_mov_b32_e32 v124, v118
	v_mov_b32_e32 v116, v112
	v_mov_b32_e32 v108, v104
	v_mov_b32_e32 v100, v98
	v_mov_b32_e32 v96, v94
	v_mov_b32_e32 v141, v103
	v_mov_b32_e32 v107, v111
	v_mov_b32_e32 v115, v121
	v_mov_b32_e32 v123, v129
	v_mov_b32_e32 v131, v137
	v_mov_b32_e32 v139, v135
	v_mov_b32_e32 v133, v127
	v_mov_b32_e32 v125, v119
	v_mov_b32_e32 v117, v113
	v_mov_b32_e32 v109, v105
	v_mov_b32_e32 v101, v99
	v_mov_b32_e32 v97, v95
	s_cmp_eq_u32 s10, 1
	s_cbranch_scc0 .Lmg_ld_done
	global_load_dwordx2 v[102:103], v[6:7], off
	global_load_dwordx2 v[110:111], v[6:7], off offset:32
	global_load_dwordx2 v[120:121], v[6:7], off offset:64
	global_load_dwordx2 v[128:129], v[6:7], off offset:96
	v_lshl_add_u64 v[6:7], v[86:87], 0, s[4:5]
	global_load_dwordx2 v[136:137], v[6:7], off
	global_load_dwordx2 v[134:135], v[6:7], off offset:32
	global_load_dwordx2 v[126:127], v[6:7], off offset:64
	global_load_dwordx2 v[118:119], v[6:7], off offset:96
	v_lshl_add_u64 v[6:7], v[88:89], 0, s[4:5]
	global_load_dwordx2 v[112:113], v[6:7], off
	global_load_dwordx2 v[104:105], v[6:7], off offset:32
	global_load_dwordx2 v[98:99], v[6:7], off offset:64
	global_load_dwordx2 v[94:95], v[6:7], off offset:96
.Lmg_ld_done:
	s_and_b64 vcc, exec, s[56:57]
	v_add_u32_e32 v67, 0x1000, v145
	v_add_u32_e32 v65, 0x2000, v145
	v_add_u32_e32 v7, 0x4000, v145
	v_add_u32_e32 v6, 0x5000, v145
	v_add_u32_e32 v5, 0x6000, v145
	v_add_u32_e32 v4, 0x7000, v145
	s_cbranch_vccnz .LBB0_114
	s_add_i32 s4, s10, s46
	s_ashr_i32 s5, s4, 31
	s_lshl_b64 s[4:5], s[4:5], 20
	s_lshl_b32 s12, s16, 1
	v_lshl_add_u64 v[176:177], v[82:83], 0, s[4:5]
	v_readfirstlane_b32 s4, v145
	v_lshl_add_u64 v[174:175], v[80:81], 0, s[12:13]
	s_mov_b32 m0, s4
	v_readfirstlane_b32 s4, v67
	s_barrier
	global_load_lds_dwordx4 v[174:175], off
	s_mov_b64 s[18:19], 0x18000
	s_mov_b32 m0, s4
	s_mov_b64 s[4:5], 0x30000
	v_lshl_add_u64 v[178:179], v[174:175], 0, s[18:19]
	v_lshl_add_u64 v[174:175], v[174:175], 0, s[4:5]
	v_readfirstlane_b32 s4, v65
	global_load_lds_dwordx4 v[178:179], off
	s_mov_b32 m0, s4
	v_readfirstlane_b32 s4, v7
	global_load_lds_dwordx4 v[174:175], off
	s_mov_b32 m0, s4
	s_mov_b64 s[4:5], 0x8000
	v_lshl_add_u64 v[174:175], v[176:177], 0, s[4:5]
	v_readfirstlane_b32 s4, v6
	global_load_lds_dwordx4 v[176:177], off
	s_mov_b32 m0, s4
	s_mov_b64 s[4:5], 0x10000
	global_load_lds_dwordx4 v[174:175], off
	v_lshl_add_u64 v[174:175], v[176:177], 0, s[4:5]
	v_readfirstlane_b32 s4, v5
	s_mov_b32 m0, s4
	v_readfirstlane_b32 s4, v4
	global_load_lds_dwordx4 v[174:175], off
	v_lshl_add_u64 v[174:175], v[176:177], 0, s[18:19]
	s_mov_b32 m0, s4
	s_nop 0
	global_load_lds_dwordx4 v[174:175], off

.LBB0_118:
	ds_read_b128 v[4:7], v150 offset:32768
	ds_read_b128 v[174:177], v150 offset:34816
	ds_read_b128 v[178:181], v150 offset:36864
	ds_read_b128 v[212:215], v151 offset:49152
	ds_read_b128 v[216:219], v151 offset:51200
	ds_read_b128 v[220:223], v151 offset:53248
	ds_read_b128 v[234:237], v151 offset:55296
	s_waitcnt lgkmcnt(0)
	v_mfma_f32_16x16x32_bf16 v[48:51], v[212:215], v[4:7], v[48:51]
	v_mfma_f32_16x16x32_bf16 v[8:11], v[216:219], v[4:7], v[8:11]
	v_mfma_f32_16x16x32_bf16 v[12:15], v[220:223], v[4:7], v[12:15]
	v_mfma_f32_16x16x32_bf16 v[4:7], v[234:237], v[4:7], v[16:19]
	v_mfma_f32_16x16x32_bf16 v[20:23], v[212:215], v[174:177], v[20:23]
	v_mfma_f32_16x16x32_bf16 v[24:27], v[216:219], v[174:177], v[24:27]
	v_mfma_f32_16x16x32_bf16 v[28:31], v[220:223], v[174:177], v[28:31]
	v_mfma_f32_16x16x32_bf16 v[32:35], v[234:237], v[174:177], v[32:35]
	v_mfma_f32_16x16x32_bf16 v[36:39], v[212:215], v[178:181], v[36:39]
	v_mfma_f32_16x16x32_bf16 v[40:43], v[216:219], v[178:181], v[40:43]
	v_mfma_f32_16x16x32_bf16 v[44:47], v[220:223], v[178:181], v[44:47]
	v_mfma_f32_16x16x32_bf16 v[174:177], v[234:237], v[178:181], v[0:3]
	ds_read_b128 v[16:19], v155 offset:32768
	ds_read_b128 v[178:181], v155 offset:34816
	ds_read_b128 v[212:215], v155 offset:36864
	ds_read_b128 v[216:219], v157 offset:49152
	ds_read_b128 v[220:223], v157 offset:51200
	ds_read_b128 v[234:237], v157 offset:53248
	ds_read_b128 v[238:241], v157 offset:55296
	s_waitcnt lgkmcnt(0)
	v_mfma_f32_16x16x32_bf16 v[0:3], v[216:219], v[16:19], v[48:51]
	s_waitcnt vmcnt(0)
	v_mfma_f32_16x16x32_bf16 v[8:11], v[220:223], v[16:19], v[8:11]
	v_mfma_f32_16x16x32_bf16 v[12:15], v[234:237], v[16:19], v[12:15]
	v_mfma_f32_16x16x32_bf16 v[16:19], v[238:241], v[16:19], v[4:7]
	v_mfma_f32_16x16x32_bf16 v[20:23], v[216:219], v[178:181], v[20:23]
	v_mfma_f32_16x16x32_bf16 v[24:27], v[220:223], v[178:181], v[24:27]
	v_mfma_f32_16x16x32_bf16 v[28:31], v[234:237], v[178:181], v[28:31]
	v_mfma_f32_16x16x32_bf16 v[32:35], v[238:241], v[178:181], v[32:35]
	v_mfma_f32_16x16x32_bf16 v[36:39], v[216:219], v[212:215], v[36:39]
	v_mfma_f32_16x16x32_bf16 v[40:43], v[220:223], v[212:215], v[40:43]
	v_mfma_f32_16x16x32_bf16 v[44:47], v[234:237], v[212:215], v[44:47]
	v_mfma_f32_16x16x32_bf16 v[4:7], v[238:241], v[212:215], v[174:177]
	s_not_b64 s[40:41], s[2:3]
	s_andn2_b64 vcc, exec, s[2:3]
	s_cbranch_vccnz .Lmg_last
	v_lshlrev_b32_e32 v65, 16, v102
	v_and_b32_e32 v67, 0xffff0000, v102
	v_lshlrev_b32_e32 v69, 16, v103
	v_and_b32_e32 v71, 0xffff0000, v103
	v_mul_f32_e32 v65, 0xbfb8aa3b, v65
	v_mul_f32_e32 v67, 0xbfb8aa3b, v67
	v_mul_f32_e32 v69, 0xbfb8aa3b, v69
	v_mul_f32_e32 v71, 0xbfb8aa3b, v71
	v_exp_f32_e32 v65, v65
	v_exp_f32_e32 v67, v67
	v_exp_f32_e32 v69, v69
	v_exp_f32_e32 v71, v71
	v_add_f32_e32 v65, 1.0, v65
	v_add_f32_e32 v67, 1.0, v67
	v_add_f32_e32 v69, 1.0, v69
	v_add_f32_e32 v71, 1.0, v71
	v_min_f32_e32 v65, 0x49742400, v65
	v_min_f32_e32 v67, 0x49742400, v67
	v_min_f32_e32 v69, 0x49742400, v69
	v_min_f32_e32 v71, 0x49742400, v71
	v_mul_f32_e32 v48, v0, v65
	v_mul_f32_e32 v49, v1, v67
	v_mul_f32_e32 v50, v2, v69
	v_mul_f32_e32 v51, v3, v71
	v_lshlrev_b32_e32 v65, 16, v140
	v_and_b32_e32 v67, 0xffff0000, v140
	v_lshlrev_b32_e32 v69, 16, v141
	v_and_b32_e32 v71, 0xffff0000, v141
	v_mul_f32_e32 v65, 0xbfb8aa3b, v65
	v_mul_f32_e32 v67, 0xbfb8aa3b, v67
	v_mul_f32_e32 v69, 0xbfb8aa3b, v69
	v_mul_f32_e32 v71, 0xbfb8aa3b, v71
	v_exp_f32_e32 v65, v65
	v_exp_f32_e32 v67, v67
	v_exp_f32_e32 v69, v69
	v_exp_f32_e32 v71, v71
	v_add_f32_e32 v65, 1.0, v65
	v_add_f32_e32 v67, 1.0, v67
	v_add_f32_e32 v69, 1.0, v69
	v_add_f32_e32 v71, 1.0, v71
	v_rcp_f32_e32 v65, v65
	v_rcp_f32_e32 v67, v67
	v_rcp_f32_e32 v69, v69
	v_rcp_f32_e32 v71, v71
	v_max_f32_e32 v65, 0x358637bd, v65
	v_max_f32_e32 v67, 0x358637bd, v67
	v_max_f32_e32 v69, 0x358637bd, v69
	v_max_f32_e32 v71, 0x358637bd, v71
	v_mul_f32_e32 v48, v48, v65
	v_mul_f32_e32 v49, v49, v67
	v_mul_f32_e32 v50, v50, v69
	v_mul_f32_e32 v51, v51, v71
	v_lshlrev_b32_e32 v65, 16, v110
	v_and_b32_e32 v67, 0xffff0000, v110
	v_lshlrev_b32_e32 v69, 16, v111
	v_and_b32_e32 v71, 0xffff0000, v111
	v_mul_f32_e32 v65, 0xbfb8aa3b, v65
	v_mul_f32_e32 v67, 0xbfb8aa3b, v67
	v_mul_f32_e32 v69, 0xbfb8aa3b, v69
	v_mul_f32_e32 v71, 0xbfb8aa3b, v71
	v_exp_f32_e32 v65, v65
	v_exp_f32_e32 v67, v67
	v_exp_f32_e32 v69, v69
	v_exp_f32_e32 v71, v71
	v_add_f32_e32 v65, 1.0, v65
	v_add_f32_e32 v67, 1.0, v67
	v_add_f32_e32 v69, 1.0, v69
	v_add_f32_e32 v71, 1.0, v71
	v_min_f32_e32 v65, 0x49742400, v65
	v_min_f32_e32 v67, 0x49742400, v67
	v_min_f32_e32 v69, 0x49742400, v69
	v_min_f32_e32 v71, 0x49742400, v71
	v_mul_f32_e32 v8, v8, v65
	v_mul_f32_e32 v9, v9, v67
	v_mul_f32_e32 v10, v10, v69
	v_mul_f32_e32 v11, v11, v71
	v_lshlrev_b32_e32 v65, 16, v106
	v_and_b32_e32 v67, 0xffff0000, v106
	v_lshlrev_b32_e32 v69, 16, v107
	v_and_b32_e32 v71, 0xffff0000, v107
	v_mul_f32_e32 v65, 0xbfb8aa3b, v65
	v_mul_f32_e32 v67, 0xbfb8aa3b, v67
	v_mul_f32_e32 v69, 0xbfb8aa3b, v69
	v_mul_f32_e32 v71, 0xbfb8aa3b, v71
	v_exp_f32_e32 v65, v65
	v_exp_f32_e32 v67, v67
	v_exp_f32_e32 v69, v69
	v_exp_f32_e32 v71, v71
	v_add_f32_e32 v65, 1.0, v65
	v_add_f32_e32 v67, 1.0, v67
	v_add_f32_e32 v69, 1.0, v69
	v_add_f32_e32 v71, 1.0, v71
	v_rcp_f32_e32 v65, v65
	v_rcp_f32_e32 v67, v67
	v_rcp_f32_e32 v69, v69
	v_rcp_f32_e32 v71, v71
	v_max_f32_e32 v65, 0x358637bd, v65
	v_max_f32_e32 v67, 0x358637bd, v67
	v_max_f32_e32 v69, 0x358637bd, v69
	v_max_f32_e32 v71, 0x358637bd, v71
	v_mul_f32_e32 v8, v8, v65
	v_mul_f32_e32 v9, v9, v67
	v_mul_f32_e32 v10, v10, v69
	v_mul_f32_e32 v11, v11, v71
	v_lshlrev_b32_e32 v65, 16, v120
	v_and_b32_e32 v67, 0xffff0000, v120
	v_lshlrev_b32_e32 v69, 16, v121
	v_and_b32_e32 v71, 0xffff0000, v121
	v_mul_f32_e32 v65, 0xbfb8aa3b, v65
	v_mul_f32_e32 v67, 0xbfb8aa3b, v67
	v_mul_f32_e32 v69, 0xbfb8aa3b, v69
	v_mul_f32_e32 v71, 0xbfb8aa3b, v71
	v_exp_f32_e32 v65, v65
	v_exp_f32_e32 v67, v67
	v_exp_f32_e32 v69, v69
	v_exp_f32_e32 v71, v71
	v_add_f32_e32 v65, 1.0, v65
	v_add_f32_e32 v67, 1.0, v67
	v_add_f32_e32 v69, 1.0, v69
	v_add_f32_e32 v71, 1.0, v71
	v_min_f32_e32 v65, 0x49742400, v65
	v_min_f32_e32 v67, 0x49742400, v67
	v_min_f32_e32 v69, 0x49742400, v69
	v_min_f32_e32 v71, 0x49742400, v71
	v_mul_f32_e32 v12, v12, v65
	v_mul_f32_e32 v13, v13, v67
	v_mul_f32_e32 v14, v14, v69
	v_mul_f32_e32 v15, v15, v71
	v_lshlrev_b32_e32 v65, 16, v114
	v_and_b32_e32 v67, 0xffff0000, v114
	v_lshlrev_b32_e32 v69, 16, v115
	v_and_b32_e32 v71, 0xffff0000, v115
	v_mul_f32_e32 v65, 0xbfb8aa3b, v65
	v_mul_f32_e32 v67, 0xbfb8aa3b, v67
	v_mul_f32_e32 v69, 0xbfb8aa3b, v69
	v_mul_f32_e32 v71, 0xbfb8aa3b, v71
	v_exp_f32_e32 v65, v65
	v_exp_f32_e32 v67, v67
	v_exp_f32_e32 v69, v69
	v_exp_f32_e32 v71, v71
	v_add_f32_e32 v65, 1.0, v65
	v_add_f32_e32 v67, 1.0, v67
	v_add_f32_e32 v69, 1.0, v69
	v_add_f32_e32 v71, 1.0, v71
	v_rcp_f32_e32 v65, v65
	v_rcp_f32_e32 v67, v67
	v_rcp_f32_e32 v69, v69
	v_rcp_f32_e32 v71, v71
	v_max_f32_e32 v65, 0x358637bd, v65
	v_max_f32_e32 v67, 0x358637bd, v67
	v_max_f32_e32 v69, 0x358637bd, v69
	v_max_f32_e32 v71, 0x358637bd, v71
	v_mul_f32_e32 v12, v12, v65
	v_mul_f32_e32 v13, v13, v67
	v_mul_f32_e32 v14, v14, v69
	v_mul_f32_e32 v15, v15, v71
	v_lshlrev_b32_e32 v65, 16, v128
	v_and_b32_e32 v67, 0xffff0000, v128
	v_lshlrev_b32_e32 v69, 16, v129
	v_and_b32_e32 v71, 0xffff0000, v129
	v_mul_f32_e32 v65, 0xbfb8aa3b, v65
	v_mul_f32_e32 v67, 0xbfb8aa3b, v67
	v_mul_f32_e32 v69, 0xbfb8aa3b, v69
	v_mul_f32_e32 v71, 0xbfb8aa3b, v71
	v_exp_f32_e32 v65, v65
	v_exp_f32_e32 v67, v67
	v_exp_f32_e32 v69, v69
	v_exp_f32_e32 v71, v71
	v_add_f32_e32 v65, 1.0, v65
	v_add_f32_e32 v67, 1.0, v67
	v_add_f32_e32 v69, 1.0, v69
	v_add_f32_e32 v71, 1.0, v71
	v_min_f32_e32 v65, 0x49742400, v65
	v_min_f32_e32 v67, 0x49742400, v67
	v_min_f32_e32 v69, 0x49742400, v69
	v_min_f32_e32 v71, 0x49742400, v71
	v_mul_f32_e32 v16, v16, v65
	v_mul_f32_e32 v17, v17, v67
	v_mul_f32_e32 v18, v18, v69
	v_mul_f32_e32 v19, v19, v71
	v_lshlrev_b32_e32 v65, 16, v122
	v_and_b32_e32 v67, 0xffff0000, v122
	v_lshlrev_b32_e32 v69, 16, v123
	v_and_b32_e32 v71, 0xffff0000, v123
	v_mul_f32_e32 v65, 0xbfb8aa3b, v65
	v_mul_f32_e32 v67, 0xbfb8aa3b, v67
	v_mul_f32_e32 v69, 0xbfb8aa3b, v69
	v_mul_f32_e32 v71, 0xbfb8aa3b, v71
	v_exp_f32_e32 v65, v65
	v_exp_f32_e32 v67, v67
	v_exp_f32_e32 v69, v69
	v_exp_f32_e32 v71, v71
	v_add_f32_e32 v65, 1.0, v65
	v_add_f32_e32 v67, 1.0, v67
	v_add_f32_e32 v69, 1.0, v69
	v_add_f32_e32 v71, 1.0, v71
	v_rcp_f32_e32 v65, v65
	v_rcp_f32_e32 v67, v67
	v_rcp_f32_e32 v69, v69
	v_rcp_f32_e32 v71, v71
	v_max_f32_e32 v65, 0x358637bd, v65
	v_max_f32_e32 v67, 0x358637bd, v67
	v_max_f32_e32 v69, 0x358637bd, v69
	v_max_f32_e32 v71, 0x358637bd, v71
	v_mul_f32_e32 v16, v16, v65
	v_mul_f32_e32 v17, v17, v67
	v_mul_f32_e32 v18, v18, v69
	v_mul_f32_e32 v19, v19, v71
	v_lshlrev_b32_e32 v65, 16, v136
	v_and_b32_e32 v67, 0xffff0000, v136
	v_lshlrev_b32_e32 v69, 16, v137
	v_and_b32_e32 v71, 0xffff0000, v137
	v_mul_f32_e32 v65, 0xbfb8aa3b, v65
	v_mul_f32_e32 v67, 0xbfb8aa3b, v67
	v_mul_f32_e32 v69, 0xbfb8aa3b, v69
	v_mul_f32_e32 v71, 0xbfb8aa3b, v71
	v_exp_f32_e32 v65, v65
	v_exp_f32_e32 v67, v67
	v_exp_f32_e32 v69, v69
	v_exp_f32_e32 v71, v71
	v_add_f32_e32 v65, 1.0, v65
	v_add_f32_e32 v67, 1.0, v67
	v_add_f32_e32 v69, 1.0, v69
	v_add_f32_e32 v71, 1.0, v71
	v_min_f32_e32 v65, 0x49742400, v65
	v_min_f32_e32 v67, 0x49742400, v67
	v_min_f32_e32 v69, 0x49742400, v69
	v_min_f32_e32 v71, 0x49742400, v71
	v_mul_f32_e32 v20, v20, v65
	v_mul_f32_e32 v21, v21, v67
	v_mul_f32_e32 v22, v22, v69
	v_mul_f32_e32 v23, v23, v71
	v_lshlrev_b32_e32 v65, 16, v130
	v_and_b32_e32 v67, 0xffff0000, v130
	v_lshlrev_b32_e32 v69, 16, v131
	v_and_b32_e32 v71, 0xffff0000, v131
	v_mul_f32_e32 v65, 0xbfb8aa3b, v65
	v_mul_f32_e32 v67, 0xbfb8aa3b, v67
	v_mul_f32_e32 v69, 0xbfb8aa3b, v69
	v_mul_f32_e32 v71, 0xbfb8aa3b, v71
	v_exp_f32_e32 v65, v65
	v_exp_f32_e32 v67, v67
	v_exp_f32_e32 v69, v69
	v_exp_f32_e32 v71, v71
	v_add_f32_e32 v65, 1.0, v65
	v_add_f32_e32 v67, 1.0, v67
	v_add_f32_e32 v69, 1.0, v69
	v_add_f32_e32 v71, 1.0, v71
	v_rcp_f32_e32 v65, v65
	v_rcp_f32_e32 v67, v67
	v_rcp_f32_e32 v69, v69
	v_rcp_f32_e32 v71, v71
	v_max_f32_e32 v65, 0x358637bd, v65
	v_max_f32_e32 v67, 0x358637bd, v67
	v_max_f32_e32 v69, 0x358637bd, v69
	v_max_f32_e32 v71, 0x358637bd, v71
	v_mul_f32_e32 v20, v20, v65
	v_mul_f32_e32 v21, v21, v67
	v_mul_f32_e32 v22, v22, v69
	v_mul_f32_e32 v23, v23, v71
	v_lshlrev_b32_e32 v65, 16, v134
	v_and_b32_e32 v67, 0xffff0000, v134
	v_lshlrev_b32_e32 v69, 16, v135
	v_and_b32_e32 v71, 0xffff0000, v135
	v_mul_f32_e32 v65, 0xbfb8aa3b, v65
	v_mul_f32_e32 v67, 0xbfb8aa3b, v67
	v_mul_f32_e32 v69, 0xbfb8aa3b, v69
	v_mul_f32_e32 v71, 0xbfb8aa3b, v71
	v_exp_f32_e32 v65, v65
	v_exp_f32_e32 v67, v67
	v_exp_f32_e32 v69, v69
	v_exp_f32_e32 v71, v71
	v_add_f32_e32 v65, 1.0, v65
	v_add_f32_e32 v67, 1.0, v67
	v_add_f32_e32 v69, 1.0, v69
	v_add_f32_e32 v71, 1.0, v71
	v_min_f32_e32 v65, 0x49742400, v65
	v_min_f32_e32 v67, 0x49742400, v67
	v_min_f32_e32 v69, 0x49742400, v69
	v_min_f32_e32 v71, 0x49742400, v71
	v_mul_f32_e32 v24, v24, v65
	v_mul_f32_e32 v25, v25, v67
	v_mul_f32_e32 v26, v26, v69
	v_mul_f32_e32 v27, v27, v71
	v_lshlrev_b32_e32 v65, 16, v138
	v_and_b32_e32 v67, 0xffff0000, v138
	v_lshlrev_b32_e32 v69, 16, v139
	v_and_b32_e32 v71, 0xffff0000, v139
	v_mul_f32_e32 v65, 0xbfb8aa3b, v65
	v_mul_f32_e32 v67, 0xbfb8aa3b, v67
	v_mul_f32_e32 v69, 0xbfb8aa3b, v69
	v_mul_f32_e32 v71, 0xbfb8aa3b, v71
	v_exp_f32_e32 v65, v65
	v_exp_f32_e32 v67, v67
	v_exp_f32_e32 v69, v69
	v_exp_f32_e32 v71, v71
	v_add_f32_e32 v65, 1.0, v65
	v_add_f32_e32 v67, 1.0, v67
	v_add_f32_e32 v69, 1.0, v69
	v_add_f32_e32 v71, 1.0, v71
	v_rcp_f32_e32 v65, v65
	v_rcp_f32_e32 v67, v67
	v_rcp_f32_e32 v69, v69
	v_rcp_f32_e32 v71, v71
	v_max_f32_e32 v65, 0x358637bd, v65
	v_max_f32_e32 v67, 0x358637bd, v67
	v_max_f32_e32 v69, 0x358637bd, v69
	v_max_f32_e32 v71, 0x358637bd, v71
	v_mul_f32_e32 v24, v24, v65
	v_mul_f32_e32 v25, v25, v67
	v_mul_f32_e32 v26, v26, v69
	v_mul_f32_e32 v27, v27, v71
	v_lshlrev_b32_e32 v65, 16, v126
	v_and_b32_e32 v67, 0xffff0000, v126
	v_lshlrev_b32_e32 v69, 16, v127
	v_and_b32_e32 v71, 0xffff0000, v127
	v_mul_f32_e32 v65, 0xbfb8aa3b, v65
	v_mul_f32_e32 v67, 0xbfb8aa3b, v67
	v_mul_f32_e32 v69, 0xbfb8aa3b, v69
	v_mul_f32_e32 v71, 0xbfb8aa3b, v71
	v_exp_f32_e32 v65, v65
	v_exp_f32_e32 v67, v67
	v_exp_f32_e32 v69, v69
	v_exp_f32_e32 v71, v71
	v_add_f32_e32 v65, 1.0, v65
	v_add_f32_e32 v67, 1.0, v67
	v_add_f32_e32 v69, 1.0, v69
	v_add_f32_e32 v71, 1.0, v71
	v_min_f32_e32 v65, 0x49742400, v65
	v_min_f32_e32 v67, 0x49742400, v67
	v_min_f32_e32 v69, 0x49742400, v69
	v_min_f32_e32 v71, 0x49742400, v71
	v_mul_f32_e32 v28, v28, v65
	v_mul_f32_e32 v29, v29, v67
	v_mul_f32_e32 v30, v30, v69
	v_mul_f32_e32 v31, v31, v71
	v_lshlrev_b32_e32 v65, 16, v132
	v_and_b32_e32 v67, 0xffff0000, v132
	v_lshlrev_b32_e32 v69, 16, v133
	v_and_b32_e32 v71, 0xffff0000, v133
	v_mul_f32_e32 v65, 0xbfb8aa3b, v65
	v_mul_f32_e32 v67, 0xbfb8aa3b, v67
	v_mul_f32_e32 v69, 0xbfb8aa3b, v69
	v_mul_f32_e32 v71, 0xbfb8aa3b, v71
	v_exp_f32_e32 v65, v65
	v_exp_f32_e32 v67, v67
	v_exp_f32_e32 v69, v69
	v_exp_f32_e32 v71, v71
	v_add_f32_e32 v65, 1.0, v65
	v_add_f32_e32 v67, 1.0, v67
	v_add_f32_e32 v69, 1.0, v69
	v_add_f32_e32 v71, 1.0, v71
	v_rcp_f32_e32 v65, v65
	v_rcp_f32_e32 v67, v67
	v_rcp_f32_e32 v69, v69
	v_rcp_f32_e32 v71, v71
	v_max_f32_e32 v65, 0x358637bd, v65
	v_max_f32_e32 v67, 0x358637bd, v67
	v_max_f32_e32 v69, 0x358637bd, v69
	v_max_f32_e32 v71, 0x358637bd, v71
	v_mul_f32_e32 v28, v28, v65
	v_mul_f32_e32 v29, v29, v67
	v_mul_f32_e32 v30, v30, v69
	v_mul_f32_e32 v31, v31, v71
	v_lshlrev_b32_e32 v65, 16, v118
	v_and_b32_e32 v67, 0xffff0000, v118
	v_lshlrev_b32_e32 v69, 16, v119
	v_and_b32_e32 v71, 0xffff0000, v119
	v_mul_f32_e32 v65, 0xbfb8aa3b, v65
	v_mul_f32_e32 v67, 0xbfb8aa3b, v67
	v_mul_f32_e32 v69, 0xbfb8aa3b, v69
	v_mul_f32_e32 v71, 0xbfb8aa3b, v71
	v_exp_f32_e32 v65, v65
	v_exp_f32_e32 v67, v67
	v_exp_f32_e32 v69, v69
	v_exp_f32_e32 v71, v71
	v_add_f32_e32 v65, 1.0, v65
	v_add_f32_e32 v67, 1.0, v67
	v_add_f32_e32 v69, 1.0, v69
	v_add_f32_e32 v71, 1.0, v71
	v_min_f32_e32 v65, 0x49742400, v65
	v_min_f32_e32 v67, 0x49742400, v67
	v_min_f32_e32 v69, 0x49742400, v69
	v_min_f32_e32 v71, 0x49742400, v71
	v_mul_f32_e32 v32, v32, v65
	v_mul_f32_e32 v33, v33, v67
	v_mul_f32_e32 v34, v34, v69
	v_mul_f32_e32 v35, v35, v71
	v_lshlrev_b32_e32 v65, 16, v124
	v_and_b32_e32 v67, 0xffff0000, v124
	v_lshlrev_b32_e32 v69, 16, v125
	v_and_b32_e32 v71, 0xffff0000, v125
	v_mul_f32_e32 v65, 0xbfb8aa3b, v65
	v_mul_f32_e32 v67, 0xbfb8aa3b, v67
	v_mul_f32_e32 v69, 0xbfb8aa3b, v69
	v_mul_f32_e32 v71, 0xbfb8aa3b, v71
	v_exp_f32_e32 v65, v65
	v_exp_f32_e32 v67, v67
	v_exp_f32_e32 v69, v69
	v_exp_f32_e32 v71, v71
	v_add_f32_e32 v65, 1.0, v65
	v_add_f32_e32 v67, 1.0, v67
	v_add_f32_e32 v69, 1.0, v69
	v_add_f32_e32 v71, 1.0, v71
	v_rcp_f32_e32 v65, v65
	v_rcp_f32_e32 v67, v67
	v_rcp_f32_e32 v69, v69
	v_rcp_f32_e32 v71, v71
	v_max_f32_e32 v65, 0x358637bd, v65
	v_max_f32_e32 v67, 0x358637bd, v67
	v_max_f32_e32 v69, 0x358637bd, v69
	v_max_f32_e32 v71, 0x358637bd, v71
	v_mul_f32_e32 v32, v32, v65
	v_mul_f32_e32 v33, v33, v67
	v_mul_f32_e32 v34, v34, v69
	v_mul_f32_e32 v35, v35, v71
	v_lshlrev_b32_e32 v65, 16, v112
	v_and_b32_e32 v67, 0xffff0000, v112
	v_lshlrev_b32_e32 v69, 16, v113
	v_and_b32_e32 v71, 0xffff0000, v113
	v_mul_f32_e32 v65, 0xbfb8aa3b, v65
	v_mul_f32_e32 v67, 0xbfb8aa3b, v67
	v_mul_f32_e32 v69, 0xbfb8aa3b, v69
	v_mul_f32_e32 v71, 0xbfb8aa3b, v71
	v_exp_f32_e32 v65, v65
	v_exp_f32_e32 v67, v67
	v_exp_f32_e32 v69, v69
	v_exp_f32_e32 v71, v71
	v_add_f32_e32 v65, 1.0, v65
	v_add_f32_e32 v67, 1.0, v67
	v_add_f32_e32 v69, 1.0, v69
	v_add_f32_e32 v71, 1.0, v71
	v_min_f32_e32 v65, 0x49742400, v65
	v_min_f32_e32 v67, 0x49742400, v67
	v_min_f32_e32 v69, 0x49742400, v69
	v_min_f32_e32 v71, 0x49742400, v71
	v_mul_f32_e32 v36, v36, v65
	v_mul_f32_e32 v37, v37, v67
	v_mul_f32_e32 v38, v38, v69
	v_mul_f32_e32 v39, v39, v71
	v_lshlrev_b32_e32 v65, 16, v116
	v_and_b32_e32 v67, 0xffff0000, v116
	v_lshlrev_b32_e32 v69, 16, v117
	v_and_b32_e32 v71, 0xffff0000, v117
	v_mul_f32_e32 v65, 0xbfb8aa3b, v65
	v_mul_f32_e32 v67, 0xbfb8aa3b, v67
	v_mul_f32_e32 v69, 0xbfb8aa3b, v69
	v_mul_f32_e32 v71, 0xbfb8aa3b, v71
	v_exp_f32_e32 v65, v65
	v_exp_f32_e32 v67, v67
	v_exp_f32_e32 v69, v69
	v_exp_f32_e32 v71, v71
	v_add_f32_e32 v65, 1.0, v65
	v_add_f32_e32 v67, 1.0, v67
	v_add_f32_e32 v69, 1.0, v69
	v_add_f32_e32 v71, 1.0, v71
	v_rcp_f32_e32 v65, v65
	v_rcp_f32_e32 v67, v67
	v_rcp_f32_e32 v69, v69
	v_rcp_f32_e32 v71, v71
	v_max_f32_e32 v65, 0x358637bd, v65
	v_max_f32_e32 v67, 0x358637bd, v67
	v_max_f32_e32 v69, 0x358637bd, v69
	v_max_f32_e32 v71, 0x358637bd, v71
	v_mul_f32_e32 v36, v36, v65
	v_mul_f32_e32 v37, v37, v67
	v_mul_f32_e32 v38, v38, v69
	v_mul_f32_e32 v39, v39, v71
	v_lshlrev_b32_e32 v65, 16, v104
	v_and_b32_e32 v67, 0xffff0000, v104
	v_lshlrev_b32_e32 v69, 16, v105
	v_and_b32_e32 v71, 0xffff0000, v105
	v_mul_f32_e32 v65, 0xbfb8aa3b, v65
	v_mul_f32_e32 v67, 0xbfb8aa3b, v67
	v_mul_f32_e32 v69, 0xbfb8aa3b, v69
	v_mul_f32_e32 v71, 0xbfb8aa3b, v71
	v_exp_f32_e32 v65, v65
	v_exp_f32_e32 v67, v67
	v_exp_f32_e32 v69, v69
	v_exp_f32_e32 v71, v71
	v_add_f32_e32 v65, 1.0, v65
	v_add_f32_e32 v67, 1.0, v67
	v_add_f32_e32 v69, 1.0, v69
	v_add_f32_e32 v71, 1.0, v71
	v_min_f32_e32 v65, 0x49742400, v65
	v_min_f32_e32 v67, 0x49742400, v67
	v_min_f32_e32 v69, 0x49742400, v69
	v_min_f32_e32 v71, 0x49742400, v71
	v_mul_f32_e32 v40, v40, v65
	v_mul_f32_e32 v41, v41, v67
	v_mul_f32_e32 v42, v42, v69
	v_mul_f32_e32 v43, v43, v71
	v_lshlrev_b32_e32 v65, 16, v108
	v_and_b32_e32 v67, 0xffff0000, v108
	v_lshlrev_b32_e32 v69, 16, v109
	v_and_b32_e32 v71, 0xffff0000, v109
	v_mul_f32_e32 v65, 0xbfb8aa3b, v65
	v_mul_f32_e32 v67, 0xbfb8aa3b, v67
	v_mul_f32_e32 v69, 0xbfb8aa3b, v69
	v_mul_f32_e32 v71, 0xbfb8aa3b, v71
	v_exp_f32_e32 v65, v65
	v_exp_f32_e32 v67, v67
	v_exp_f32_e32 v69, v69
	v_exp_f32_e32 v71, v71
	v_add_f32_e32 v65, 1.0, v65
	v_add_f32_e32 v67, 1.0, v67
	v_add_f32_e32 v69, 1.0, v69
	v_add_f32_e32 v71, 1.0, v71
	v_rcp_f32_e32 v65, v65
	v_rcp_f32_e32 v67, v67
	v_rcp_f32_e32 v69, v69
	v_rcp_f32_e32 v71, v71
	v_max_f32_e32 v65, 0x358637bd, v65
	v_max_f32_e32 v67, 0x358637bd, v67
	v_max_f32_e32 v69, 0x358637bd, v69
	v_max_f32_e32 v71, 0x358637bd, v71
	v_mul_f32_e32 v40, v40, v65
	v_mul_f32_e32 v41, v41, v67
	v_mul_f32_e32 v42, v42, v69
	v_mul_f32_e32 v43, v43, v71
	v_lshlrev_b32_e32 v65, 16, v98
	v_and_b32_e32 v67, 0xffff0000, v98
	v_lshlrev_b32_e32 v69, 16, v99
	v_and_b32_e32 v71, 0xffff0000, v99
	v_mul_f32_e32 v65, 0xbfb8aa3b, v65
	v_mul_f32_e32 v67, 0xbfb8aa3b, v67
	v_mul_f32_e32 v69, 0xbfb8aa3b, v69
	v_mul_f32_e32 v71, 0xbfb8aa3b, v71
	v_exp_f32_e32 v65, v65
	v_exp_f32_e32 v67, v67
	v_exp_f32_e32 v69, v69
	v_exp_f32_e32 v71, v71
	v_add_f32_e32 v65, 1.0, v65
	v_add_f32_e32 v67, 1.0, v67
	v_add_f32_e32 v69, 1.0, v69
	v_add_f32_e32 v71, 1.0, v71
	v_min_f32_e32 v65, 0x49742400, v65
	v_min_f32_e32 v67, 0x49742400, v67
	v_min_f32_e32 v69, 0x49742400, v69
	v_min_f32_e32 v71, 0x49742400, v71
	v_mul_f32_e32 v44, v44, v65
	v_mul_f32_e32 v45, v45, v67
	v_mul_f32_e32 v46, v46, v69
	v_mul_f32_e32 v47, v47, v71
	v_lshlrev_b32_e32 v65, 16, v100
	v_and_b32_e32 v67, 0xffff0000, v100
	v_lshlrev_b32_e32 v69, 16, v101
	v_and_b32_e32 v71, 0xffff0000, v101
	v_mul_f32_e32 v65, 0xbfb8aa3b, v65
	v_mul_f32_e32 v67, 0xbfb8aa3b, v67
	v_mul_f32_e32 v69, 0xbfb8aa3b, v69
	v_mul_f32_e32 v71, 0xbfb8aa3b, v71
	v_exp_f32_e32 v65, v65
	v_exp_f32_e32 v67, v67
	v_exp_f32_e32 v69, v69
	v_exp_f32_e32 v71, v71
	v_add_f32_e32 v65, 1.0, v65
	v_add_f32_e32 v67, 1.0, v67
	v_add_f32_e32 v69, 1.0, v69
	v_add_f32_e32 v71, 1.0, v71
	v_rcp_f32_e32 v65, v65
	v_rcp_f32_e32 v67, v67
	v_rcp_f32_e32 v69, v69
	v_rcp_f32_e32 v71, v71
	v_max_f32_e32 v65, 0x358637bd, v65
	v_max_f32_e32 v67, 0x358637bd, v67
	v_max_f32_e32 v69, 0x358637bd, v69
	v_max_f32_e32 v71, 0x358637bd, v71
	v_mul_f32_e32 v44, v44, v65
	v_mul_f32_e32 v45, v45, v67
	v_mul_f32_e32 v46, v46, v69
	v_mul_f32_e32 v47, v47, v71
	v_lshlrev_b32_e32 v65, 16, v94
	v_and_b32_e32 v67, 0xffff0000, v94
	v_lshlrev_b32_e32 v69, 16, v95
	v_and_b32_e32 v71, 0xffff0000, v95
	v_mul_f32_e32 v65, 0xbfb8aa3b, v65
	v_mul_f32_e32 v67, 0xbfb8aa3b, v67
	v_mul_f32_e32 v69, 0xbfb8aa3b, v69
	v_mul_f32_e32 v71, 0xbfb8aa3b, v71
	v_exp_f32_e32 v65, v65
	v_exp_f32_e32 v67, v67
	v_exp_f32_e32 v69, v69
	v_exp_f32_e32 v71, v71
	v_add_f32_e32 v65, 1.0, v65
	v_add_f32_e32 v67, 1.0, v67
	v_add_f32_e32 v69, 1.0, v69
	v_add_f32_e32 v71, 1.0, v71
	v_min_f32_e32 v65, 0x49742400, v65
	v_min_f32_e32 v67, 0x49742400, v67
	v_min_f32_e32 v69, 0x49742400, v69
	v_min_f32_e32 v71, 0x49742400, v71
	v_mul_f32_e32 v0, v4, v65
	v_mul_f32_e32 v1, v5, v67
	v_mul_f32_e32 v2, v6, v69
	v_mul_f32_e32 v3, v7, v71
	v_lshlrev_b32_e32 v65, 16, v96
	v_and_b32_e32 v67, 0xffff0000, v96
	v_lshlrev_b32_e32 v69, 16, v97
	v_and_b32_e32 v71, 0xffff0000, v97
	v_mul_f32_e32 v65, 0xbfb8aa3b, v65
	v_mul_f32_e32 v67, 0xbfb8aa3b, v67
	v_mul_f32_e32 v69, 0xbfb8aa3b, v69
	v_mul_f32_e32 v71, 0xbfb8aa3b, v71
	v_exp_f32_e32 v65, v65
	v_exp_f32_e32 v67, v67
	v_exp_f32_e32 v69, v69
	v_exp_f32_e32 v71, v71
	v_add_f32_e32 v65, 1.0, v65
	v_add_f32_e32 v67, 1.0, v67
	v_add_f32_e32 v69, 1.0, v69
	v_add_f32_e32 v71, 1.0, v71
	v_rcp_f32_e32 v65, v65
	v_rcp_f32_e32 v67, v67
	v_rcp_f32_e32 v69, v69
	v_rcp_f32_e32 v71, v71
	v_max_f32_e32 v65, 0x358637bd, v65
	v_max_f32_e32 v67, 0x358637bd, v67
	v_max_f32_e32 v69, 0x358637bd, v69
	v_max_f32_e32 v71, 0x358637bd, v71
	v_mul_f32_e32 v0, v0, v65
	v_mul_f32_e32 v1, v1, v67
	v_mul_f32_e32 v2, v2, v69
	v_mul_f32_e32 v3, v3, v71
	s_branch .LBB0_111
.Lmg_last:
	v_lshlrev_b32_e32 v65, 16, v140
	v_and_b32_e32 v67, 0xffff0000, v140
	v_lshlrev_b32_e32 v69, 16, v141
	v_and_b32_e32 v71, 0xffff0000, v141
	v_mul_f32_e32 v65, 0xbfb8aa3b, v65
	v_mul_f32_e32 v67, 0xbfb8aa3b, v67
	v_mul_f32_e32 v69, 0xbfb8aa3b, v69
	v_mul_f32_e32 v71, 0xbfb8aa3b, v71
	v_exp_f32_e32 v65, v65
	v_exp_f32_e32 v67, v67
	v_exp_f32_e32 v69, v69
	v_exp_f32_e32 v71, v71
	v_add_f32_e32 v65, 1.0, v65
	v_add_f32_e32 v67, 1.0, v67
	v_add_f32_e32 v69, 1.0, v69
	v_add_f32_e32 v71, 1.0, v71
	v_rcp_f32_e32 v65, v65
	v_rcp_f32_e32 v67, v67
	v_rcp_f32_e32 v69, v69
	v_rcp_f32_e32 v71, v71
	v_max_f32_e32 v65, 0x358637bd, v65
	v_max_f32_e32 v67, 0x358637bd, v67
	v_max_f32_e32 v69, 0x358637bd, v69
	v_max_f32_e32 v71, 0x358637bd, v71
	v_mul_f32_e32 v48, v0, v65
	v_mul_f32_e32 v49, v1, v67
	v_mul_f32_e32 v50, v2, v69
	v_mul_f32_e32 v51, v3, v71
	v_lshlrev_b32_e32 v65, 16, v106
	v_and_b32_e32 v67, 0xffff0000, v106
	v_lshlrev_b32_e32 v69, 16, v107
	v_and_b32_e32 v71, 0xffff0000, v107
	v_mul_f32_e32 v65, 0xbfb8aa3b, v65
	v_mul_f32_e32 v67, 0xbfb8aa3b, v67
	v_mul_f32_e32 v69, 0xbfb8aa3b, v69
	v_mul_f32_e32 v71, 0xbfb8aa3b, v71
	v_exp_f32_e32 v65, v65
	v_exp_f32_e32 v67, v67
	v_exp_f32_e32 v69, v69
	v_exp_f32_e32 v71, v71
	v_add_f32_e32 v65, 1.0, v65
	v_add_f32_e32 v67, 1.0, v67
	v_add_f32_e32 v69, 1.0, v69
	v_add_f32_e32 v71, 1.0, v71
	v_rcp_f32_e32 v65, v65
	v_rcp_f32_e32 v67, v67
	v_rcp_f32_e32 v69, v69
	v_rcp_f32_e32 v71, v71
	v_max_f32_e32 v65, 0x358637bd, v65
	v_max_f32_e32 v67, 0x358637bd, v67
	v_max_f32_e32 v69, 0x358637bd, v69
	v_max_f32_e32 v71, 0x358637bd, v71
	v_mul_f32_e32 v8, v8, v65
	v_mul_f32_e32 v9, v9, v67
	v_mul_f32_e32 v10, v10, v69
	v_mul_f32_e32 v11, v11, v71
	v_lshlrev_b32_e32 v65, 16, v114
	v_and_b32_e32 v67, 0xffff0000, v114
	v_lshlrev_b32_e32 v69, 16, v115
	v_and_b32_e32 v71, 0xffff0000, v115
	v_mul_f32_e32 v65, 0xbfb8aa3b, v65
	v_mul_f32_e32 v67, 0xbfb8aa3b, v67
	v_mul_f32_e32 v69, 0xbfb8aa3b, v69
	v_mul_f32_e32 v71, 0xbfb8aa3b, v71
	v_exp_f32_e32 v65, v65
	v_exp_f32_e32 v67, v67
	v_exp_f32_e32 v69, v69
	v_exp_f32_e32 v71, v71
	v_add_f32_e32 v65, 1.0, v65
	v_add_f32_e32 v67, 1.0, v67
	v_add_f32_e32 v69, 1.0, v69
	v_add_f32_e32 v71, 1.0, v71
	v_rcp_f32_e32 v65, v65
	v_rcp_f32_e32 v67, v67
	v_rcp_f32_e32 v69, v69
	v_rcp_f32_e32 v71, v71
	v_max_f32_e32 v65, 0x358637bd, v65
	v_max_f32_e32 v67, 0x358637bd, v67
	v_max_f32_e32 v69, 0x358637bd, v69
	v_max_f32_e32 v71, 0x358637bd, v71
	v_mul_f32_e32 v12, v12, v65
	v_mul_f32_e32 v13, v13, v67
	v_mul_f32_e32 v14, v14, v69
	v_mul_f32_e32 v15, v15, v71
	v_lshlrev_b32_e32 v65, 16, v122
	v_and_b32_e32 v67, 0xffff0000, v122
	v_lshlrev_b32_e32 v69, 16, v123
	v_and_b32_e32 v71, 0xffff0000, v123
	v_mul_f32_e32 v65, 0xbfb8aa3b, v65
	v_mul_f32_e32 v67, 0xbfb8aa3b, v67
	v_mul_f32_e32 v69, 0xbfb8aa3b, v69
	v_mul_f32_e32 v71, 0xbfb8aa3b, v71
	v_exp_f32_e32 v65, v65
	v_exp_f32_e32 v67, v67
	v_exp_f32_e32 v69, v69
	v_exp_f32_e32 v71, v71
	v_add_f32_e32 v65, 1.0, v65
	v_add_f32_e32 v67, 1.0, v67
	v_add_f32_e32 v69, 1.0, v69
	v_add_f32_e32 v71, 1.0, v71
	v_rcp_f32_e32 v65, v65
	v_rcp_f32_e32 v67, v67
	v_rcp_f32_e32 v69, v69
	v_rcp_f32_e32 v71, v71
	v_max_f32_e32 v65, 0x358637bd, v65
	v_max_f32_e32 v67, 0x358637bd, v67
	v_max_f32_e32 v69, 0x358637bd, v69
	v_max_f32_e32 v71, 0x358637bd, v71
	v_mul_f32_e32 v16, v16, v65
	v_mul_f32_e32 v17, v17, v67
	v_mul_f32_e32 v18, v18, v69
	v_mul_f32_e32 v19, v19, v71
	v_lshlrev_b32_e32 v65, 16, v130
	v_and_b32_e32 v67, 0xffff0000, v130
	v_lshlrev_b32_e32 v69, 16, v131
	v_and_b32_e32 v71, 0xffff0000, v131
	v_mul_f32_e32 v65, 0xbfb8aa3b, v65
	v_mul_f32_e32 v67, 0xbfb8aa3b, v67
	v_mul_f32_e32 v69, 0xbfb8aa3b, v69
	v_mul_f32_e32 v71, 0xbfb8aa3b, v71
	v_exp_f32_e32 v65, v65
	v_exp_f32_e32 v67, v67
	v_exp_f32_e32 v69, v69
	v_exp_f32_e32 v71, v71
	v_add_f32_e32 v65, 1.0, v65
	v_add_f32_e32 v67, 1.0, v67
	v_add_f32_e32 v69, 1.0, v69
	v_add_f32_e32 v71, 1.0, v71
	v_rcp_f32_e32 v65, v65
	v_rcp_f32_e32 v67, v67
	v_rcp_f32_e32 v69, v69
	v_rcp_f32_e32 v71, v71
	v_max_f32_e32 v65, 0x358637bd, v65
	v_max_f32_e32 v67, 0x358637bd, v67
	v_max_f32_e32 v69, 0x358637bd, v69
	v_max_f32_e32 v71, 0x358637bd, v71
	v_mul_f32_e32 v20, v20, v65
	v_mul_f32_e32 v21, v21, v67
	v_mul_f32_e32 v22, v22, v69
	v_mul_f32_e32 v23, v23, v71
	v_lshlrev_b32_e32 v65, 16, v138
	v_and_b32_e32 v67, 0xffff0000, v138
	v_lshlrev_b32_e32 v69, 16, v139
	v_and_b32_e32 v71, 0xffff0000, v139
	v_mul_f32_e32 v65, 0xbfb8aa3b, v65
	v_mul_f32_e32 v67, 0xbfb8aa3b, v67
	v_mul_f32_e32 v69, 0xbfb8aa3b, v69
	v_mul_f32_e32 v71, 0xbfb8aa3b, v71
	v_exp_f32_e32 v65, v65
	v_exp_f32_e32 v67, v67
	v_exp_f32_e32 v69, v69
	v_exp_f32_e32 v71, v71
	v_add_f32_e32 v65, 1.0, v65
	v_add_f32_e32 v67, 1.0, v67
	v_add_f32_e32 v69, 1.0, v69
	v_add_f32_e32 v71, 1.0, v71
	v_rcp_f32_e32 v65, v65
	v_rcp_f32_e32 v67, v67
	v_rcp_f32_e32 v69, v69
	v_rcp_f32_e32 v71, v71
	v_max_f32_e32 v65, 0x358637bd, v65
	v_max_f32_e32 v67, 0x358637bd, v67
	v_max_f32_e32 v69, 0x358637bd, v69
	v_max_f32_e32 v71, 0x358637bd, v71
	v_mul_f32_e32 v24, v24, v65
	v_mul_f32_e32 v25, v25, v67
	v_mul_f32_e32 v26, v26, v69
	v_mul_f32_e32 v27, v27, v71
	v_lshlrev_b32_e32 v65, 16, v132
	v_and_b32_e32 v67, 0xffff0000, v132
	v_lshlrev_b32_e32 v69, 16, v133
	v_and_b32_e32 v71, 0xffff0000, v133
	v_mul_f32_e32 v65, 0xbfb8aa3b, v65
	v_mul_f32_e32 v67, 0xbfb8aa3b, v67
	v_mul_f32_e32 v69, 0xbfb8aa3b, v69
	v_mul_f32_e32 v71, 0xbfb8aa3b, v71
	v_exp_f32_e32 v65, v65
	v_exp_f32_e32 v67, v67
	v_exp_f32_e32 v69, v69
	v_exp_f32_e32 v71, v71
	v_add_f32_e32 v65, 1.0, v65
	v_add_f32_e32 v67, 1.0, v67
	v_add_f32_e32 v69, 1.0, v69
	v_add_f32_e32 v71, 1.0, v71
	v_rcp_f32_e32 v65, v65
	v_rcp_f32_e32 v67, v67
	v_rcp_f32_e32 v69, v69
	v_rcp_f32_e32 v71, v71
	v_max_f32_e32 v65, 0x358637bd, v65
	v_max_f32_e32 v67, 0x358637bd, v67
	v_max_f32_e32 v69, 0x358637bd, v69
	v_max_f32_e32 v71, 0x358637bd, v71
	v_mul_f32_e32 v28, v28, v65
	v_mul_f32_e32 v29, v29, v67
	v_mul_f32_e32 v30, v30, v69
	v_mul_f32_e32 v31, v31, v71
	v_lshlrev_b32_e32 v65, 16, v124
	v_and_b32_e32 v67, 0xffff0000, v124
	v_lshlrev_b32_e32 v69, 16, v125
	v_and_b32_e32 v71, 0xffff0000, v125
	v_mul_f32_e32 v65, 0xbfb8aa3b, v65
	v_mul_f32_e32 v67, 0xbfb8aa3b, v67
	v_mul_f32_e32 v69, 0xbfb8aa3b, v69
	v_mul_f32_e32 v71, 0xbfb8aa3b, v71
	v_exp_f32_e32 v65, v65
	v_exp_f32_e32 v67, v67
	v_exp_f32_e32 v69, v69
	v_exp_f32_e32 v71, v71
	v_add_f32_e32 v65, 1.0, v65
	v_add_f32_e32 v67, 1.0, v67
	v_add_f32_e32 v69, 1.0, v69
	v_add_f32_e32 v71, 1.0, v71
	v_rcp_f32_e32 v65, v65
	v_rcp_f32_e32 v67, v67
	v_rcp_f32_e32 v69, v69
	v_rcp_f32_e32 v71, v71
	v_max_f32_e32 v65, 0x358637bd, v65
	v_max_f32_e32 v67, 0x358637bd, v67
	v_max_f32_e32 v69, 0x358637bd, v69
	v_max_f32_e32 v71, 0x358637bd, v71
	v_mul_f32_e32 v32, v32, v65
	v_mul_f32_e32 v33, v33, v67
	v_mul_f32_e32 v34, v34, v69
	v_mul_f32_e32 v35, v35, v71
	v_lshlrev_b32_e32 v65, 16, v116
	v_and_b32_e32 v67, 0xffff0000, v116
	v_lshlrev_b32_e32 v69, 16, v117
	v_and_b32_e32 v71, 0xffff0000, v117
	v_mul_f32_e32 v65, 0xbfb8aa3b, v65
	v_mul_f32_e32 v67, 0xbfb8aa3b, v67
	v_mul_f32_e32 v69, 0xbfb8aa3b, v69
	v_mul_f32_e32 v71, 0xbfb8aa3b, v71
	v_exp_f32_e32 v65, v65
	v_exp_f32_e32 v67, v67
	v_exp_f32_e32 v69, v69
	v_exp_f32_e32 v71, v71
	v_add_f32_e32 v65, 1.0, v65
	v_add_f32_e32 v67, 1.0, v67
	v_add_f32_e32 v69, 1.0, v69
	v_add_f32_e32 v71, 1.0, v71
	v_rcp_f32_e32 v65, v65
	v_rcp_f32_e32 v67, v67
	v_rcp_f32_e32 v69, v69
	v_rcp_f32_e32 v71, v71
	v_max_f32_e32 v65, 0x358637bd, v65
	v_max_f32_e32 v67, 0x358637bd, v67
	v_max_f32_e32 v69, 0x358637bd, v69
	v_max_f32_e32 v71, 0x358637bd, v71
	v_mul_f32_e32 v36, v36, v65
	v_mul_f32_e32 v37, v37, v67
	v_mul_f32_e32 v38, v38, v69
	v_mul_f32_e32 v39, v39, v71
	v_lshlrev_b32_e32 v65, 16, v108
	v_and_b32_e32 v67, 0xffff0000, v108
	v_lshlrev_b32_e32 v69, 16, v109
	v_and_b32_e32 v71, 0xffff0000, v109
	v_mul_f32_e32 v65, 0xbfb8aa3b, v65
	v_mul_f32_e32 v67, 0xbfb8aa3b, v67
	v_mul_f32_e32 v69, 0xbfb8aa3b, v69
	v_mul_f32_e32 v71, 0xbfb8aa3b, v71
	v_exp_f32_e32 v65, v65
	v_exp_f32_e32 v67, v67
	v_exp_f32_e32 v69, v69
	v_exp_f32_e32 v71, v71
	v_add_f32_e32 v65, 1.0, v65
	v_add_f32_e32 v67, 1.0, v67
	v_add_f32_e32 v69, 1.0, v69
	v_add_f32_e32 v71, 1.0, v71
	v_rcp_f32_e32 v65, v65
	v_rcp_f32_e32 v67, v67
	v_rcp_f32_e32 v69, v69
	v_rcp_f32_e32 v71, v71
	v_max_f32_e32 v65, 0x358637bd, v65
	v_max_f32_e32 v67, 0x358637bd, v67
	v_max_f32_e32 v69, 0x358637bd, v69
	v_max_f32_e32 v71, 0x358637bd, v71
	v_mul_f32_e32 v40, v40, v65
	v_mul_f32_e32 v41, v41, v67
	v_mul_f32_e32 v42, v42, v69
	v_mul_f32_e32 v43, v43, v71
	v_lshlrev_b32_e32 v65, 16, v100
	v_and_b32_e32 v67, 0xffff0000, v100
	v_lshlrev_b32_e32 v69, 16, v101
	v_and_b32_e32 v71, 0xffff0000, v101
	v_mul_f32_e32 v65, 0xbfb8aa3b, v65
	v_mul_f32_e32 v67, 0xbfb8aa3b, v67
	v_mul_f32_e32 v69, 0xbfb8aa3b, v69
	v_mul_f32_e32 v71, 0xbfb8aa3b, v71
	v_exp_f32_e32 v65, v65
	v_exp_f32_e32 v67, v67
	v_exp_f32_e32 v69, v69
	v_exp_f32_e32 v71, v71
	v_add_f32_e32 v65, 1.0, v65
	v_add_f32_e32 v67, 1.0, v67
	v_add_f32_e32 v69, 1.0, v69
	v_add_f32_e32 v71, 1.0, v71
	v_rcp_f32_e32 v65, v65
	v_rcp_f32_e32 v67, v67
	v_rcp_f32_e32 v69, v69
	v_rcp_f32_e32 v71, v71
	v_max_f32_e32 v65, 0x358637bd, v65
	v_max_f32_e32 v67, 0x358637bd, v67
	v_max_f32_e32 v69, 0x358637bd, v69
	v_max_f32_e32 v71, 0x358637bd, v71
	v_mul_f32_e32 v44, v44, v65
	v_mul_f32_e32 v45, v45, v67
	v_mul_f32_e32 v46, v46, v69
	v_mul_f32_e32 v47, v47, v71
	v_lshlrev_b32_e32 v65, 16, v96
	v_and_b32_e32 v67, 0xffff0000, v96
	v_lshlrev_b32_e32 v69, 16, v97
	v_and_b32_e32 v71, 0xffff0000, v97
	v_mul_f32_e32 v65, 0xbfb8aa3b, v65
	v_mul_f32_e32 v67, 0xbfb8aa3b, v67
	v_mul_f32_e32 v69, 0xbfb8aa3b, v69
	v_mul_f32_e32 v71, 0xbfb8aa3b, v71
	v_exp_f32_e32 v65, v65
	v_exp_f32_e32 v67, v67
	v_exp_f32_e32 v69, v69
	v_exp_f32_e32 v71, v71
	v_add_f32_e32 v65, 1.0, v65
	v_add_f32_e32 v67, 1.0, v67
	v_add_f32_e32 v69, 1.0, v69
	v_add_f32_e32 v71, 1.0, v71
	v_rcp_f32_e32 v65, v65
	v_rcp_f32_e32 v67, v67
	v_rcp_f32_e32 v69, v69
	v_rcp_f32_e32 v71, v71
	v_max_f32_e32 v65, 0x358637bd, v65
	v_max_f32_e32 v67, 0x358637bd, v67
	v_max_f32_e32 v69, 0x358637bd, v69
	v_max_f32_e32 v71, 0x358637bd, v71
	v_mul_f32_e32 v0, v4, v65
	v_mul_f32_e32 v1, v5, v67
	v_mul_f32_e32 v2, v6, v69
	v_mul_f32_e32 v3, v7, v71
	s_branch .LBB0_111

.LBB0_143:
	s_and_b64 vcc, exec, s[0:1]
	s_cbranch_vccz .LBB0_149
	v_readlane_b32 s0, v249, 47
	v_readlane_b32 s1, v249, 48
	s_waitcnt vmcnt(0) lgkmcnt(0)
	v_mov_b32_e32 v0, v167
	s_andn2_b64 vcc, exec, s[0:1]
	s_cbranch_vccnz .LBB0_149
	v_and_b32_e32 v120, 31, v167
	v_bfe_u32 v121, v167, 5, 1
	v_lshrrev_b32_e32 v122, 6, v167
	v_lshlrev_b32_e32 v123, 4, v121
	v_lshl_add_u32 v124, v120, 7, v123
	v_lshl_add_u32 v125, v122, 12, v124
	v_lshlrev_b32_e32 v126, 3, v121
	v_lshl_add_u32 v126, v122, 6, v126
	v_lshl_add_u32 v127, v120, 10, v126
	v_lshl_add_u32 v128, v122, 7, v123
	v_mul_u32_u24_e32 v129, 0x3700, v120
	v_add_u32_e32 v129, v129, v126
	v_mul_u32_u24_e32 v130, 0xc00, v120
	v_add_u32_e32 v130, v130, v126
	v_xor_b32_e32 v131, 32, v186
	v_lshlrev_b32_e32 v131, 2, v131
	v_lshl_add_u32 v132, v122, 5, v120
	v_lshlrev_b32_e32 v132, 2, v132
	v_lshlrev_b32_e32 v133, 2, v120
	v_readlane_b32 s10, v249, 0
	v_readlane_b32 s0, v249, 7
	v_readlane_b32 s1, v249, 8
	s_load_dword s11, s[0:1], 0x0
	s_waitcnt lgkmcnt(0)
.Lgo_item:
	s_lshr_b32 s12, s10, 2
	s_and_b32 s14, s10, 3
	s_lshl_b32 s15, s10, 13
	v_readlane_b32 s0, v249, 49
	v_readlane_b32 s1, v249, 50
	s_add_u32 s0, s0, s15
	s_addc_u32 s1, s1, 0
	s_lshl_b32 s15, s10, 15
	v_readlane_b32 s2, v249, 51
	v_readlane_b32 s3, v249, 52
	s_add_u32 s2, s2, s15
	s_addc_u32 s3, s3, 0
	global_load_dwordx4 v[16:19], v124, s[0:1] offset:0
	global_load_dwordx4 v[48:51], v125, s[2:3] offset:0
	global_load_dwordx4 v[20:23], v124, s[0:1] offset:32
	global_load_dwordx4 v[52:55], v125, s[2:3] offset:32
	global_load_dwordx4 v[24:27], v124, s[0:1] offset:64
	global_load_dwordx4 v[56:59], v125, s[2:3] offset:64
	global_load_dwordx4 v[28:31], v124, s[0:1] offset:96
	global_load_dwordx4 v[60:63], v125, s[2:3] offset:96
	s_add_u32 s4, s0, 0x1000
	s_addc_u32 s5, s1, 0
	global_load_dwordx4 v[32:35], v124, s[4:5] offset:0
	s_add_u32 s6, s2, 0x4000
	s_addc_u32 s7, s3, 0
	global_load_dwordx4 v[64:67], v125, s[6:7] offset:0
	global_load_dwordx4 v[36:39], v124, s[4:5] offset:32
	global_load_dwordx4 v[68:71], v125, s[6:7] offset:32
	global_load_dwordx4 v[40:43], v124, s[4:5] offset:64
	global_load_dwordx4 v[72:75], v125, s[6:7] offset:64
	global_load_dwordx4 v[44:47], v124, s[4:5] offset:96
	global_load_dwordx4 v[76:79], v125, s[6:7] offset:96
	s_lshl_b32 s15, s12, 15
	s_lshl_b32 s16, s14, 8
	s_add_i32 s15, s15, s16
	v_readlane_b32 s4, v249, 43
	v_readlane_b32 s5, v249, 44
	s_add_u32 s4, s4, s15
	s_addc_u32 s5, s5, 0
	v_readlane_b32 s6, v249, 45
	v_readlane_b32 s7, v249, 46
	s_add_u32 s6, s6, s15
	s_addc_u32 s7, s7, 0
	global_load_dwordx2 v[80:81], v127, s[4:5]
	global_load_dwordx2 v[88:89], v127, s[6:7]
	global_load_dwordx2 v[82:83], v127, s[4:5] offset:16
	global_load_dwordx2 v[90:91], v127, s[6:7] offset:16
	global_load_dwordx2 v[84:85], v127, s[4:5] offset:32
	global_load_dwordx2 v[92:93], v127, s[6:7] offset:32
	global_load_dwordx2 v[86:87], v127, s[4:5] offset:48
	global_load_dwordx2 v[94:95], v127, s[6:7] offset:48
	v_readlane_b32 s4, v249, 53
	v_readlane_b32 s5, v249, 54
	s_lshl_b32 s15, s28, 9
	s_add_u32 s4, s4, s15
	s_addc_u32 s5, s5, 0
	global_load_dwordx4 v[96:99], v128, s[4:5]
	global_load_dwordx4 v[100:103], v128, s[4:5] offset:32
	global_load_dwordx4 v[104:107], v128, s[4:5] offset:64
	global_load_dwordx4 v[108:111], v128, s[4:5] offset:96
	s_mul_i32 s15, s12, 0x6e000
	s_add_i32 s15, s15, s16
	s_add_i32 s15, s15, 0x800
	s_add_u32 s4, s60, s15
	s_addc_u32 s5, s61, 0
	global_load_dwordx2 v[112:113], v129, s[4:5]
	global_load_dwordx2 v[114:115], v129, s[4:5] offset:16
	global_load_dwordx2 v[116:117], v129, s[4:5] offset:32
	global_load_dwordx2 v[118:119], v129, s[4:5] offset:48
	s_waitcnt vmcnt(30)
	v_mfma_f32_32x32x16_bf16 v[0:15], v[48:51], v[16:19], 0
	s_waitcnt vmcnt(28)
	v_mfma_f32_32x32x16_bf16 v[0:15], v[52:55], v[20:23], v[0:15]
	s_waitcnt vmcnt(26)
	v_mfma_f32_32x32x16_bf16 v[0:15], v[56:59], v[24:27], v[0:15]
	s_waitcnt vmcnt(24)
	v_mfma_f32_32x32x16_bf16 v[0:15], v[60:63], v[28:31], v[0:15]
	s_waitcnt vmcnt(22)
	v_mfma_f32_32x32x16_bf16 v[0:15], v[64:67], v[32:35], v[0:15]
	s_waitcnt vmcnt(20)
	v_mfma_f32_32x32x16_bf16 v[0:15], v[68:71], v[36:39], v[0:15]
	s_waitcnt vmcnt(18)
	v_mfma_f32_32x32x16_bf16 v[0:15], v[72:75], v[40:43], v[0:15]
	s_waitcnt vmcnt(16)
	v_mfma_f32_32x32x16_bf16 v[0:15], v[76:79], v[44:47], v[0:15]
	s_waitcnt vmcnt(8)
	v_lshlrev_b32_e32 v134, 16, v80
	v_and_b32_e32 v135, 0xffff0000, v80
	v_lshlrev_b32_e32 v136, 16, v81
	v_and_b32_e32 v137, 0xffff0000, v81
	v_lshlrev_b32_e32 v150, 16, v88
	v_and_b32_e32 v151, 0xffff0000, v88
	v_add_f32_e32 v134, v134, v150
	v_add_f32_e32 v135, v135, v151
	v_lshlrev_b32_e32 v150, 16, v89
	v_and_b32_e32 v151, 0xffff0000, v89
	v_add_f32_e32 v136, v136, v150
	v_add_f32_e32 v137, v137, v151
	v_lshlrev_b32_e32 v138, 16, v82
	v_and_b32_e32 v139, 0xffff0000, v82
	v_lshlrev_b32_e32 v140, 16, v83
	v_and_b32_e32 v141, 0xffff0000, v83
	v_lshlrev_b32_e32 v150, 16, v90
	v_and_b32_e32 v151, 0xffff0000, v90
	v_add_f32_e32 v138, v138, v150
	v_add_f32_e32 v139, v139, v151
	v_lshlrev_b32_e32 v150, 16, v91
	v_and_b32_e32 v151, 0xffff0000, v91
	v_add_f32_e32 v140, v140, v150
	v_add_f32_e32 v141, v141, v151
	v_lshlrev_b32_e32 v142, 16, v84
	v_and_b32_e32 v143, 0xffff0000, v84
	v_lshlrev_b32_e32 v144, 16, v85
	v_and_b32_e32 v145, 0xffff0000, v85
	v_lshlrev_b32_e32 v150, 16, v92
	v_and_b32_e32 v151, 0xffff0000, v92
	v_add_f32_e32 v142, v142, v150
	v_add_f32_e32 v143, v143, v151
	v_lshlrev_b32_e32 v150, 16, v93
	v_and_b32_e32 v151, 0xffff0000, v93
	v_add_f32_e32 v144, v144, v150
	v_add_f32_e32 v145, v145, v151
	v_lshlrev_b32_e32 v146, 16, v86
	v_and_b32_e32 v147, 0xffff0000, v86
	v_lshlrev_b32_e32 v148, 16, v87
	v_and_b32_e32 v149, 0xffff0000, v87
	v_lshlrev_b32_e32 v150, 16, v94
	v_and_b32_e32 v151, 0xffff0000, v94
	v_add_f32_e32 v146, v146, v150
	v_add_f32_e32 v147, v147, v151
	v_lshlrev_b32_e32 v150, 16, v95
	v_and_b32_e32 v151, 0xffff0000, v95
	v_add_f32_e32 v148, v148, v150
	v_add_f32_e32 v149, v149, v151
	v_mov_b32_e32 v150, 0
	v_add_f32_e32 v0, v0, v134
	v_fmac_f32_e32 v150, v0, v0
	v_add_f32_e32 v1, v1, v135
	v_fmac_f32_e32 v150, v1, v1
	v_add_f32_e32 v2, v2, v136
	v_fmac_f32_e32 v150, v2, v2
	v_add_f32_e32 v3, v3, v137
	v_fmac_f32_e32 v150, v3, v3
	v_add_f32_e32 v4, v4, v138
	v_fmac_f32_e32 v150, v4, v4
	v_add_f32_e32 v5, v5, v139
	v_fmac_f32_e32 v150, v5, v5
	v_add_f32_e32 v6, v6, v140
	v_fmac_f32_e32 v150, v6, v6
	v_add_f32_e32 v7, v7, v141
	v_fmac_f32_e32 v150, v7, v7
	v_add_f32_e32 v8, v8, v142
	v_fmac_f32_e32 v150, v8, v8
	v_add_f32_e32 v9, v9, v143
	v_fmac_f32_e32 v150, v9, v9
	v_add_f32_e32 v10, v10, v144
	v_fmac_f32_e32 v150, v10, v10
	v_add_f32_e32 v11, v11, v145
	v_fmac_f32_e32 v150, v11, v11
	v_add_f32_e32 v12, v12, v146
	v_fmac_f32_e32 v150, v12, v12
	v_add_f32_e32 v13, v13, v147
	v_fmac_f32_e32 v150, v13, v13
	v_add_f32_e32 v14, v14, v148
	v_fmac_f32_e32 v150, v14, v14
	v_add_f32_e32 v15, v15, v149
	v_fmac_f32_e32 v150, v15, v15
	ds_bpermute_b32 v151, v131, v150
	s_waitcnt lgkmcnt(0)
	v_add_f32_e32 v150, v150, v151
	s_barrier
	v_cmp_eq_u32_e32 vcc, 0, v121
	s_and_saveexec_b64 s[6:7], vcc
	ds_write_b32 v132, v150
	s_or_b64 exec, exec, s[6:7]
	s_waitcnt lgkmcnt(0)
	s_barrier
	ds_read_b32 v134, v133
	ds_read_b32 v135, v133 offset:128
	ds_read_b32 v136, v133 offset:256
	ds_read_b32 v137, v133 offset:384
	s_waitcnt lgkmcnt(0)
	v_add_f32_e32 v134, v134, v135
	v_add_f32_e32 v134, v134, v136
	v_add_f32_e32 v134, v134, v137
	v_fmamk_f32 v134, v134, 0x3c000000, v171
	s_mov_b32 s15, 0x800000
	v_cmp_gt_f32_e32 vcc, s15, v134
	v_mul_f32_e32 v135, 0x4b800000, v134
	s_nop 0
	v_cndmask_b32_e32 v134, v134, v135, vcc
	v_rsq_f32_e32 v134, v134
	s_nop 0
	v_mul_f32_e32 v135, 0x45800000, v134
	v_cndmask_b32_e32 v134, v134, v135, vcc
	s_waitcnt vmcnt(0)
	s_mul_i32 s15, s12, 0x18000
	s_add_i32 s15, s15, s16
	v_readlane_b32 s4, v249, 39
	v_readlane_b32 s5, v249, 40
	s_add_u32 s4, s4, s15
	s_addc_u32 s5, s5, 0
	v_lshlrev_b32_e32 v140, 16, v112
	v_and_b32_e32 v141, 0xffff0000, v112
	v_lshlrev_b32_e32 v142, 16, v113
	v_and_b32_e32 v143, 0xffff0000, v113
	v_mul_f32_e32 v136, 0xbfb8aa3b, v140
	v_mul_f32_e32 v137, 0xbfb8aa3b, v141
	v_mul_f32_e32 v138, 0xbfb8aa3b, v142
	v_mul_f32_e32 v139, 0xbfb8aa3b, v143
	v_exp_f32_e32 v136, v136
	v_exp_f32_e32 v137, v137
	v_exp_f32_e32 v138, v138
	v_exp_f32_e32 v139, v139
	v_add_f32_e32 v136, 1.0, v136
	v_add_f32_e32 v137, 1.0, v137
	v_add_f32_e32 v138, 1.0, v138
	v_add_f32_e32 v139, 1.0, v139
	v_rcp_f32_e32 v136, v136
	v_rcp_f32_e32 v137, v137
	v_rcp_f32_e32 v138, v138
	v_rcp_f32_e32 v139, v139
	v_mul_f32_e32 v136, v140, v136
	v_mul_f32_e32 v137, v141, v137
	v_mul_f32_e32 v138, v142, v138
	v_mul_f32_e32 v139, v143, v139
	v_mul_f32_e32 v0, v0, v134
	v_mul_f32_e32 v0, v96, v0
	v_mul_f32_e32 v0, v136, v0
	v_mul_f32_e32 v1, v1, v134
	v_mul_f32_e32 v1, v97, v1
	v_mul_f32_e32 v1, v137, v1
	v_mul_f32_e32 v2, v2, v134
	v_mul_f32_e32 v2, v98, v2
	v_mul_f32_e32 v2, v138, v2
	v_mul_f32_e32 v3, v3, v134
	v_mul_f32_e32 v3, v99, v3
	v_mul_f32_e32 v3, v139, v3
	v_cvt_pk_bf16_f32 v144, v0, v1
	v_cvt_pk_bf16_f32 v145, v2, v3
	global_store_dwordx2 v130, v[144:145], s[4:5]
	v_lshlrev_b32_e32 v140, 16, v114
	v_and_b32_e32 v141, 0xffff0000, v114
	v_lshlrev_b32_e32 v142, 16, v115
	v_and_b32_e32 v143, 0xffff0000, v115
	v_mul_f32_e32 v136, 0xbfb8aa3b, v140
	v_mul_f32_e32 v137, 0xbfb8aa3b, v141
	v_mul_f32_e32 v138, 0xbfb8aa3b, v142
	v_mul_f32_e32 v139, 0xbfb8aa3b, v143
	v_exp_f32_e32 v136, v136
	v_exp_f32_e32 v137, v137
	v_exp_f32_e32 v138, v138
	v_exp_f32_e32 v139, v139
	v_add_f32_e32 v136, 1.0, v136
	v_add_f32_e32 v137, 1.0, v137
	v_add_f32_e32 v138, 1.0, v138
	v_add_f32_e32 v139, 1.0, v139
	v_rcp_f32_e32 v136, v136
	v_rcp_f32_e32 v137, v137
	v_rcp_f32_e32 v138, v138
	v_rcp_f32_e32 v139, v139
	v_mul_f32_e32 v136, v140, v136
	v_mul_f32_e32 v137, v141, v137
	v_mul_f32_e32 v138, v142, v138
	v_mul_f32_e32 v139, v143, v139
	v_mul_f32_e32 v4, v4, v134
	v_mul_f32_e32 v4, v100, v4
	v_mul_f32_e32 v4, v136, v4
	v_mul_f32_e32 v5, v5, v134
	v_mul_f32_e32 v5, v101, v5
	v_mul_f32_e32 v5, v137, v5
	v_mul_f32_e32 v6, v6, v134
	v_mul_f32_e32 v6, v102, v6
	v_mul_f32_e32 v6, v138, v6
	v_mul_f32_e32 v7, v7, v134
	v_mul_f32_e32 v7, v103, v7
	v_mul_f32_e32 v7, v139, v7
	v_cvt_pk_bf16_f32 v144, v4, v5
	v_cvt_pk_bf16_f32 v145, v6, v7
	global_store_dwordx2 v130, v[144:145], s[4:5] offset:16
	v_lshlrev_b32_e32 v140, 16, v116
	v_and_b32_e32 v141, 0xffff0000, v116
	v_lshlrev_b32_e32 v142, 16, v117
	v_and_b32_e32 v143, 0xffff0000, v117
	v_mul_f32_e32 v136, 0xbfb8aa3b, v140
	v_mul_f32_e32 v137, 0xbfb8aa3b, v141
	v_mul_f32_e32 v138, 0xbfb8aa3b, v142
	v_mul_f32_e32 v139, 0xbfb8aa3b, v143
	v_exp_f32_e32 v136, v136
	v_exp_f32_e32 v137, v137
	v_exp_f32_e32 v138, v138
	v_exp_f32_e32 v139, v139
	v_add_f32_e32 v136, 1.0, v136
	v_add_f32_e32 v137, 1.0, v137
	v_add_f32_e32 v138, 1.0, v138
	v_add_f32_e32 v139, 1.0, v139
	v_rcp_f32_e32 v136, v136
	v_rcp_f32_e32 v137, v137
	v_rcp_f32_e32 v138, v138
	v_rcp_f32_e32 v139, v139
	v_mul_f32_e32 v136, v140, v136
	v_mul_f32_e32 v137, v141, v137
	v_mul_f32_e32 v138, v142, v138
	v_mul_f32_e32 v139, v143, v139
	v_mul_f32_e32 v8, v8, v134
	v_mul_f32_e32 v8, v104, v8
	v_mul_f32_e32 v8, v136, v8
	v_mul_f32_e32 v9, v9, v134
	v_mul_f32_e32 v9, v105, v9
	v_mul_f32_e32 v9, v137, v9
	v_mul_f32_e32 v10, v10, v134
	v_mul_f32_e32 v10, v106, v10
	v_mul_f32_e32 v10, v138, v10
	v_mul_f32_e32 v11, v11, v134
	v_mul_f32_e32 v11, v107, v11
	v_mul_f32_e32 v11, v139, v11
	v_cvt_pk_bf16_f32 v144, v8, v9
	v_cvt_pk_bf16_f32 v145, v10, v11
	global_store_dwordx2 v130, v[144:145], s[4:5] offset:32
	v_lshlrev_b32_e32 v140, 16, v118
	v_and_b32_e32 v141, 0xffff0000, v118
	v_lshlrev_b32_e32 v142, 16, v119
	v_and_b32_e32 v143, 0xffff0000, v119
	v_mul_f32_e32 v136, 0xbfb8aa3b, v140
	v_mul_f32_e32 v137, 0xbfb8aa3b, v141
	v_mul_f32_e32 v138, 0xbfb8aa3b, v142
	v_mul_f32_e32 v139, 0xbfb8aa3b, v143
	v_exp_f32_e32 v136, v136
	v_exp_f32_e32 v137, v137
	v_exp_f32_e32 v138, v138
	v_exp_f32_e32 v139, v139
	v_add_f32_e32 v136, 1.0, v136
	v_add_f32_e32 v137, 1.0, v137
	v_add_f32_e32 v138, 1.0, v138
	v_add_f32_e32 v139, 1.0, v139
	v_rcp_f32_e32 v136, v136
	v_rcp_f32_e32 v137, v137
	v_rcp_f32_e32 v138, v138
	v_rcp_f32_e32 v139, v139
	v_mul_f32_e32 v136, v140, v136
	v_mul_f32_e32 v137, v141, v137
	v_mul_f32_e32 v138, v142, v138
	v_mul_f32_e32 v139, v143, v139
	v_mul_f32_e32 v12, v12, v134
	v_mul_f32_e32 v12, v108, v12
	v_mul_f32_e32 v12, v136, v12
	v_mul_f32_e32 v13, v13, v134
	v_mul_f32_e32 v13, v109, v13
	v_mul_f32_e32 v13, v137, v13
	v_mul_f32_e32 v14, v14, v134
	v_mul_f32_e32 v14, v110, v14
	v_mul_f32_e32 v14, v138, v14
	v_mul_f32_e32 v15, v15, v134
	v_mul_f32_e32 v15, v111, v15
	v_mul_f32_e32 v15, v139, v15
	v_cvt_pk_bf16_f32 v144, v12, v13
	v_cvt_pk_bf16_f32 v145, v14, v15
	global_store_dwordx2 v130, v[144:145], s[4:5] offset:48
	s_add_i32 s10, s10, s11
	s_cmpk_lt_i32 s10, 0x300
	s_cbranch_scc1 .Lgo_item
